# v33 plus grid-barrier poll interval s_sleep 1 -> s_sleep 4 (fewer sc1 polls on the shared counter while stragglers finish)
# baseline (speedup 1.0000x reference)
.LBB0_239:
	s_sleep 4
	global_load_dword v3, v1, s[4:5] offset:32 sc1
	s_waitcnt vmcnt(0)
	v_and_b32_e32 v3, 0xffff0000, v3
	v_cmp_ne_u32_e32 vcc, v3, v2
	s_or_b64 s[6:7], vcc, s[6:7]
	s_andn2_b64 exec, exec, s[6:7]
	s_cbranch_execnz .LBB0_239

.LBB0_4741:
	s_sleep 4
	global_load_dword v2, v0, s[2:3] offset:32 sc1
	s_waitcnt vmcnt(0)
	v_and_b32_e32 v2, 0xffff0000, v2
	v_cmp_ne_u32_e32 vcc, v2, v1
	s_or_b64 s[4:5], vcc, s[4:5]
	s_andn2_b64 exec, exec, s[4:5]
	s_cbranch_execnz .LBB0_4741
